# P1 SwiGLU epilogue hand-written; its ai=1 half interleaved into the next unit's first MFMA block (same wave), ai=0 half at the unit boundary
# baseline (speedup 1.0000x reference)
.LBB0_131:
	s_mov_b32 s99, 0
	s_cmp_lt_i32 s60, 2
	s_cselect_b64 s[6:7], -1, 0
	s_waitcnt lgkmcnt(0)
	s_add_u32 s24, s30, 0xe000000
	s_addc_u32 s25, s31, 0
	s_and_b64 s[6:7], s[6:7], s[0:1]
	s_andn2_b64 vcc, exec, s[6:7]
	v_writelane_b32 v254, s71, 10
	s_cbranch_vccnz .LBB0_148
	s_cmpk_gt_i32 s2, 0x1b7f
	s_cbranch_scc1 .LBB0_148
	s_add_u32 s54, s30, 0x100000
	s_addc_u32 s55, s31, 0
	v_mbcnt_hi_u32_b32 v10, -1, v228
	s_lshl_b32 s56, s71, 10
	v_lshl_add_u32 v0, v10, 4, s56
	v_add_u32_e32 v1, 0x2000, v0
	v_ashrrev_i32_e32 v2, 31, v1
	v_lshrrev_b32_e32 v2, 22, v2
	v_add_u32_e32 v2, v1, v2
	v_ashrrev_i32_e32 v8, 10, v2
	v_mul_i32_i24_e32 v2, 0x400, v8
	v_sub_u32_e32 v1, v1, v2
	v_lshrrev_b32_e32 v2, 4, v1
	v_bitop3_b32 v1, v2, v1, 32 bitop3:0x6c
	v_ashrrev_i32_e32 v2, 31, v1
	v_lshrrev_b32_e32 v2, 26, v2
	v_add_u32_e32 v2, v1, v2
	v_ashrrev_i32_e32 v9, 6, v2
	v_lshlrev_b32_e32 v3, 3, v8
	v_and_b32_e32 v2, 0xffc0, v2
	v_and_b32_e32 v3, -16, v3
	v_sub_u32_e32 v1, v1, v2
	v_add_u32_e32 v3, v9, v3
	v_lshrrev_b16_e32 v2, 7, v1
	v_and_b32_e32 v4, 3, v9
	s_mov_b32 s0, 0x1fffe0
	v_lshrrev_b32_e32 v5, 2, v3
	v_lshlrev_b32_e32 v6, 1, v3
	v_and_b32_e32 v2, 1, v2
	v_and_or_b32 v4, v3, s0, v4
	v_and_b32_e32 v5, 4, v5
	v_and_b32_e32 v6, 24, v6
	v_add_u16_e32 v1, v1, v2
	v_mov_b32_e32 v2, 1
	v_or3_b32 v4, v4, v5, v6
	v_lshlrev_b32_e32 v5, 5, v8
	v_ashrrev_i16_sdwa v1, v2, sext(v1) dst_sel:DWORD dst_unused:UNUSED_PAD src0_sel:DWORD src1_sel:BYTE_0
	v_and_b32_e32 v5, 32, v5
	v_bfe_i32 v11, v1, 0, 16
	v_add_lshl_u32 v1, v5, v11, 1
	v_lshl_add_u32 v128, v4, 11, v1
	v_lshl_add_u32 v130, v3, 11, v1
	v_ashrrev_i32_e32 v1, 31, v0
	v_lshrrev_b32_e32 v1, 22, v1
	v_add_u32_e32 v1, v0, v1
	v_ashrrev_i32_e32 v12, 10, v1
	v_mul_i32_i24_e32 v1, 0x400, v12
	v_sub_u32_e32 v0, v0, v1
	v_lshrrev_b32_e32 v1, 4, v0
	v_bitop3_b32 v0, v1, v0, 32 bitop3:0x6c
	v_ashrrev_i32_e32 v1, 31, v0
	v_lshrrev_b32_e32 v1, 26, v1
	v_add_u32_e32 v1, v0, v1
	v_lshlrev_b32_e32 v3, 3, v12
	v_ashrrev_i32_e32 v13, 6, v1
	v_and_b32_e32 v3, -16, v3
	v_add_u32_e32 v3, v13, v3
	v_and_b32_e32 v4, 3, v13
	s_ashr_i32 s57, s2, 31
	v_and_or_b32 v4, v3, s0, v4
	s_lshr_b32 s0, s57, 29
	s_add_i32 s0, s2, s0
	s_ashr_i32 s8, s0, 3
	s_and_b32 s0, s0, -8
	s_lshr_b32 s1, s3, 8
	s_sub_i32 s0, s2, s0
	s_cmp_lt_i32 s0, 0
	s_movk_i32 s58, 0x371
	s_cselect_b32 s9, s58, 0x370
	s_mul_i32 s0, s0, s9
	s_add_i32 s0, s0, s8
	s_mul_hi_i32 s8, s0, 0x2e8ba2e9
	s_lshr_b32 s9, s8, 31
	s_ashr_i32 s8, s8, 5
	s_add_i32 s8, s8, s9
	s_lshl_b32 s9, s8, 3
	s_mulk_i32 s8, 0xb0
	s_sub_i32 s8, s0, s8
	s_sext_i32_i16 s0, s8
	s_bfe_u32 s0, s0, 0x3001c
	s_add_i32 s10, s8, s0
	s_sext_i32_i16 s0, s10
	s_and_b32 s10, s10, 0xfff8
	s_sub_i32 s8, s8, s10
	s_sext_i32_i16 s8, s8
	v_lshrrev_b32_e32 v5, 2, v3
	v_lshlrev_b32_e32 v6, 1, v3
	v_and_b32_e32 v1, 0xc0, v1
	s_lshr_b32 s0, s0, 3
	s_add_i32 s46, s9, s8
	v_and_b32_e32 v5, 4, v5
	v_and_b32_e32 v6, 24, v6
	v_sub_u32_e32 v0, v0, v1
	s_ashr_i32 s47, s46, 31
	s_bfe_i64 s[10:11], s[0:1], 0x100000
	v_or3_b32 v4, v4, v5, v6
	v_lshlrev_b32_e32 v5, 5, v12
	v_ashrrev_i16_sdwa v0, v2, sext(v0) dst_sel:DWORD dst_unused:UNUSED_PAD src0_sel:DWORD src1_sel:BYTE_0
	s_lshl_b64 s[8:9], s[46:47], 19
	s_lshl_b64 s[10:11], s[10:11], 19
	v_and_b32_e32 v5, 32, v5
	v_bfe_i32 v14, v0, 0, 16
	s_add_u32 s50, s54, s10
	v_add_lshl_u32 v0, v5, v14, 1
	s_addc_u32 s51, s55, s11
	s_add_i32 s47, s56, 0
	v_lshl_add_u32 v132, v4, 11, v0
	s_add_i32 m0, s47, 0x10000
	v_lshl_add_u32 v134, v3, 11, v0
	global_load_lds_dwordx4 v132, s[50:51]
	s_add_i32 m0, s47, 0x12000
	s_add_u32 s10, s50, 0x40000
	global_load_lds_dwordx4 v128, s[50:51]
	s_addc_u32 s11, s51, 0
	s_add_i32 m0, s47, 0x14000
	v_mov_b32_e32 v133, 0
	global_load_lds_dwordx4 v132, s[10:11]
	s_add_i32 m0, s47, 0x16000
	s_add_u32 s48, s62, s8
	s_addc_u32 s49, s63, s9
	s_add_i32 s59, s47, 0x2000
	global_load_lds_dwordx4 v128, s[10:11]
	s_mov_b32 m0, s47
	s_add_u32 s8, s48, 0x40000
	global_load_lds_dwordx4 v134, s[48:49]
	s_mov_b32 m0, s59
	s_addc_u32 s9, s49, 0
	s_add_i32 s66, s47, 0x4000
	global_load_lds_dwordx4 v130, s[48:49]
	s_mov_b32 m0, s66
	s_add_i32 s67, s47, 0x6000
	global_load_lds_dwordx4 v134, s[8:9]
	s_mov_b32 m0, s67
	v_mov_b32_e32 v129, v133
	global_load_lds_dwordx4 v130, s[8:9]
	v_mov_b32_e32 v135, v133
	v_mov_b32_e32 v131, v133
	s_cmp_eq_u32 s1, 1
	s_mov_b32 s68, 0
	v_lshl_add_u64 v[6:7], s[50:51], 0, v[132:133]
	v_lshl_add_u64 v[4:5], s[50:51], 0, v[128:129]
	v_lshl_add_u64 v[0:1], s[48:49], 0, v[134:135]
	s_cselect_b64 s[8:9], -1, 0
	s_cmp_lg_u32 s1, 1
	v_lshl_add_u64 v[2:3], s[48:49], 0, v[130:131]
	s_cbranch_scc1 .LBB0_135
	s_barrier

.LBB0_140:
	s_ashr_i32 s37, s36, 31
	s_lshl_b64 s[42:43], s[36:37], 19
	s_add_u32 s42, s62, s42
	s_addc_u32 s43, s63, s43
	s_and_b64 s[44:45], s[0:1], exec
	s_cselect_b32 s37, s43, s49
	s_cselect_b32 s77, s42, s48
	s_ashr_i32 s39, s38, 31
	s_lshl_b64 s[44:45], s[38:39], 19
	s_add_u32 s44, s54, s44
	s_addc_u32 s45, s55, s45
	s_and_b64 s[52:53], s[0:1], exec
	s_cselect_b32 s39, s45, s51
	s_cselect_b32 s78, s44, s50
	s_add_u32 s48, s48, 0x40080
	s_addc_u32 s49, s49, 0
	s_add_u32 s79, s50, 0x100
	s_addc_u32 s80, s51, 0
	s_mov_b32 s81, -2
	ds_read_b128 v[150:153], v147
	ds_read_b128 v[154:157], v147 offset:1024
	ds_read_b128 v[158:161], v147 offset:2048
	ds_read_b128 v[162:165], v147 offset:3072
	ds_read_b128 v[166:169], v148
	ds_read_b128 v[170:173], v148 offset:1024
	ds_read_b128 v[174:177], v148 offset:2048
	ds_read_b128 v[178:181], v148 offset:3072
	s_add_u32 s50, s48, 0xfffc0080
	s_addc_u32 s51, s49, -1
	s_cmp_eq_u32 s81, 12
	s_cselect_b32 s53, s37, s51
	s_cselect_b32 s52, s77, s50
	s_cselect_b32 s51, s39, s80
	s_cselect_b32 s50, s78, s79
	v_lshl_add_u64 v[214:215], s[48:49], 0, v[136:137]
	s_add_i32 m0, s47, 0xc000
	ds_read_b128 v[182:185], v149
	ds_read_b128 v[186:189], v149 offset:1024
	ds_read_b128 v[190:193], v149 offset:2048
	ds_read_b128 v[194:197], v149 offset:3072
	ds_read_b128 v[198:201], v149 offset:4096
	ds_read_b128 v[202:205], v149 offset:5120
	ds_read_b128 v[206:209], v149 offset:6144
	ds_read_b128 v[210:213], v149 offset:7168
	global_load_lds_dwordx4 v[214:215], off
	v_lshl_add_u64 v[214:215], s[48:49], 0, v[138:139]
	s_add_i32 m0, s47, 0xe000
	s_nop 0
	global_load_lds_dwordx4 v[214:215], off
	s_waitcnt vmcnt(8)
	s_waitcnt lgkmcnt(0)
	s_cmp_eq_u32 s99, 1
	s_cbranch_scc1 .Lsw1_fused
	s_setprio 1
	s_barrier
	v_mfma_f32_16x16x32_bf16 v[124:127], v[150:153], v[182:185], 0
	v_mfma_f32_16x16x32_bf16 v[116:119], v[158:161], v[182:185], 0
	v_mfma_f32_16x16x32_bf16 v[108:111], v[150:153], v[190:193], 0
	v_mfma_f32_16x16x32_bf16 v[100:103], v[158:161], v[190:193], 0
	v_mfma_f32_16x16x32_bf16 v[92:95], v[150:153], v[198:201], 0
	v_mfma_f32_16x16x32_bf16 v[84:87], v[158:161], v[198:201], 0
	v_mfma_f32_16x16x32_bf16 v[76:79], v[150:153], v[206:209], 0
	v_mfma_f32_16x16x32_bf16 v[68:71], v[158:161], v[206:209], 0
	v_mfma_f32_16x16x32_bf16 v[124:127], v[154:157], v[186:189], v[124:127]
	v_mfma_f32_16x16x32_bf16 v[116:119], v[162:165], v[186:189], v[116:119]
	v_mfma_f32_16x16x32_bf16 v[108:111], v[154:157], v[194:197], v[108:111]
	v_mfma_f32_16x16x32_bf16 v[100:103], v[162:165], v[194:197], v[100:103]
	v_mfma_f32_16x16x32_bf16 v[92:95], v[154:157], v[202:205], v[92:95]
	v_mfma_f32_16x16x32_bf16 v[84:87], v[162:165], v[202:205], v[84:87]
	v_mfma_f32_16x16x32_bf16 v[76:79], v[154:157], v[210:213], v[76:79]
	v_mfma_f32_16x16x32_bf16 v[68:71], v[162:165], v[210:213], v[68:71]
	v_mfma_f32_16x16x32_bf16 v[120:123], v[166:169], v[182:185], 0
	v_mfma_f32_16x16x32_bf16 v[112:115], v[174:177], v[182:185], 0
	v_mfma_f32_16x16x32_bf16 v[104:107], v[166:169], v[190:193], 0
	v_mfma_f32_16x16x32_bf16 v[96:99], v[174:177], v[190:193], 0
	v_mfma_f32_16x16x32_bf16 v[88:91], v[166:169], v[198:201], 0
	v_mfma_f32_16x16x32_bf16 v[80:83], v[174:177], v[198:201], 0
	v_mfma_f32_16x16x32_bf16 v[72:75], v[166:169], v[206:209], 0
	v_mfma_f32_16x16x32_bf16 v[64:67], v[174:177], v[206:209], 0
	v_mfma_f32_16x16x32_bf16 v[120:123], v[170:173], v[186:189], v[120:123]
	v_mfma_f32_16x16x32_bf16 v[112:115], v[178:181], v[186:189], v[112:115]
	v_mfma_f32_16x16x32_bf16 v[104:107], v[170:173], v[194:197], v[104:107]
	v_mfma_f32_16x16x32_bf16 v[96:99], v[178:181], v[194:197], v[96:99]
	v_mfma_f32_16x16x32_bf16 v[88:91], v[170:173], v[202:205], v[88:91]
	v_mfma_f32_16x16x32_bf16 v[80:83], v[178:181], v[202:205], v[80:83]
	v_mfma_f32_16x16x32_bf16 v[72:75], v[170:173], v[210:213], v[72:75]
	v_mfma_f32_16x16x32_bf16 v[64:67], v[178:181], v[210:213], v[64:67]
	s_barrier
	s_setprio 0
	s_branch .Lsw1_join
.Lsw1_fused:
	s_setprio 1
	s_barrier
	v_mfma_f32_16x16x32_bf16 v[124:127], v[150:153], v[182:185], 0
	v_exp_f32_e64 v230, -v60
	v_exp_f32_e64 v231, -v61
	v_exp_f32_e64 v232, -v62
	v_exp_f32_e64 v233, -v63
	v_mfma_f32_16x16x32_bf16 v[116:119], v[158:161], v[182:185], 0
	v_exp_f32_e64 v234, -v52
	v_exp_f32_e64 v235, -v53
	v_exp_f32_e64 v236, -v54
	v_exp_f32_e64 v237, -v55
	v_pk_mul_f32 v[56:57], v[60:61], v[56:57]
	v_mfma_f32_16x16x32_bf16 v[108:111], v[150:153], v[190:193], 0
	v_pk_mul_f32 v[58:59], v[62:63], v[58:59]
	v_pk_mul_f32 v[48:49], v[52:53], v[48:49]
	v_pk_mul_f32 v[50:51], v[54:55], v[50:51]
	v_pk_add_f32 v[230:231], v[230:231], 1.0 op_sel_hi:[1,0]
	v_pk_add_f32 v[232:233], v[232:233], 1.0 op_sel_hi:[1,0]
	v_mfma_f32_16x16x32_bf16 v[100:103], v[158:161], v[190:193], 0
	v_pk_add_f32 v[234:235], v[234:235], 1.0 op_sel_hi:[1,0]
	v_pk_add_f32 v[236:237], v[236:237], 1.0 op_sel_hi:[1,0]
	v_rcp_f32_e32 v230, v230
	v_rcp_f32_e32 v231, v231
	v_mfma_f32_16x16x32_bf16 v[92:95], v[150:153], v[198:201], 0
	v_rcp_f32_e32 v232, v232
	v_rcp_f32_e32 v233, v233
	v_rcp_f32_e32 v234, v234
	v_rcp_f32_e32 v235, v235
	v_rcp_f32_e32 v236, v236
	v_mfma_f32_16x16x32_bf16 v[84:87], v[158:161], v[198:201], 0
	v_rcp_f32_e32 v237, v237
	s_add_u32 vcc_lo, s100, 0xb0000
	s_addc_u32 vcc_hi, s101, 0
	v_pk_mul_f32 v[56:57], v[230:231], v[56:57]
	v_pk_mul_f32 v[58:59], v[232:233], v[58:59]
	v_mfma_f32_16x16x32_bf16 v[76:79], v[150:153], v[206:209], 0
	v_pk_mul_f32 v[48:49], v[234:235], v[48:49]
	v_pk_mul_f32 v[50:51], v[236:237], v[50:51]
	v_cvt_pk_bf16_f32 v238, v56, v57
	v_cvt_pk_bf16_f32 v239, v58, v59
	v_mfma_f32_16x16x32_bf16 v[68:71], v[158:161], v[206:209], 0
	v_cvt_pk_bf16_f32 v240, v48, v49
	v_cvt_pk_bf16_f32 v241, v50, v51
	global_store_dwordx4 v224, v[238:241], vcc
	v_exp_f32_e64 v242, -v44
	v_exp_f32_e64 v243, -v45
	v_mfma_f32_16x16x32_bf16 v[124:127], v[154:157], v[186:189], v[124:127]
	v_exp_f32_e64 v244, -v46
	v_exp_f32_e64 v245, -v47
	v_exp_f32_e64 v246, -v36
	v_exp_f32_e64 v247, -v37
	v_exp_f32_e64 v248, -v38
	v_mfma_f32_16x16x32_bf16 v[116:119], v[162:165], v[186:189], v[116:119]
	v_exp_f32_e64 v249, -v39
	v_pk_mul_f32 v[40:41], v[44:45], v[40:41]
	v_pk_mul_f32 v[42:43], v[46:47], v[42:43]
	v_pk_mul_f32 v[32:33], v[36:37], v[32:33]
	v_mfma_f32_16x16x32_bf16 v[108:111], v[154:157], v[194:197], v[108:111]
	v_pk_mul_f32 v[34:35], v[38:39], v[34:35]
	v_pk_add_f32 v[242:243], v[242:243], 1.0 op_sel_hi:[1,0]
	v_pk_add_f32 v[244:245], v[244:245], 1.0 op_sel_hi:[1,0]
	v_pk_add_f32 v[246:247], v[246:247], 1.0 op_sel_hi:[1,0]
	v_pk_add_f32 v[248:249], v[248:249], 1.0 op_sel_hi:[1,0]
	v_mfma_f32_16x16x32_bf16 v[100:103], v[162:165], v[194:197], v[100:103]
	v_rcp_f32_e32 v242, v242
	v_rcp_f32_e32 v243, v243
	v_rcp_f32_e32 v244, v244
	v_rcp_f32_e32 v245, v245
	v_rcp_f32_e32 v246, v246
	v_mfma_f32_16x16x32_bf16 v[92:95], v[154:157], v[202:205], v[92:95]
	v_rcp_f32_e32 v247, v247
	v_rcp_f32_e32 v248, v248
	v_rcp_f32_e32 v249, v249
	s_add_u32 vcc_lo, s100, 0xc6000
	v_mfma_f32_16x16x32_bf16 v[84:87], v[162:165], v[202:205], v[84:87]
	s_addc_u32 vcc_hi, s101, 0
	v_pk_mul_f32 v[40:41], v[242:243], v[40:41]
	v_pk_mul_f32 v[42:43], v[244:245], v[42:43]
	v_pk_mul_f32 v[32:33], v[246:247], v[32:33]
	v_pk_mul_f32 v[34:35], v[248:249], v[34:35]
	v_mfma_f32_16x16x32_bf16 v[76:79], v[154:157], v[210:213], v[76:79]
	v_cvt_pk_bf16_f32 v250, v40, v41
	v_cvt_pk_bf16_f32 v251, v42, v43
	v_cvt_pk_bf16_f32 v252, v32, v33
	v_cvt_pk_bf16_f32 v253, v34, v35
	global_store_dwordx4 v224, v[250:253], vcc
	v_mfma_f32_16x16x32_bf16 v[68:71], v[162:165], v[210:213], v[68:71]
	v_exp_f32_e64 v230, -v28
	v_exp_f32_e64 v231, -v29
	v_exp_f32_e64 v232, -v30
	v_exp_f32_e64 v233, -v31
	v_mfma_f32_16x16x32_bf16 v[120:123], v[166:169], v[182:185], 0
	v_exp_f32_e64 v234, -v20
	v_exp_f32_e64 v235, -v21
	v_exp_f32_e64 v236, -v22
	v_exp_f32_e64 v237, -v23
	v_pk_mul_f32 v[24:25], v[28:29], v[24:25]
	v_mfma_f32_16x16x32_bf16 v[112:115], v[174:177], v[182:185], 0
	v_pk_mul_f32 v[26:27], v[30:31], v[26:27]
	v_pk_mul_f32 v[16:17], v[20:21], v[16:17]
	v_pk_mul_f32 v[18:19], v[22:23], v[18:19]
	v_pk_add_f32 v[230:231], v[230:231], 1.0 op_sel_hi:[1,0]
	v_pk_add_f32 v[232:233], v[232:233], 1.0 op_sel_hi:[1,0]
	v_mfma_f32_16x16x32_bf16 v[104:107], v[166:169], v[190:193], 0
	v_pk_add_f32 v[234:235], v[234:235], 1.0 op_sel_hi:[1,0]
	v_pk_add_f32 v[236:237], v[236:237], 1.0 op_sel_hi:[1,0]
	v_rcp_f32_e32 v230, v230
	v_rcp_f32_e32 v231, v231
	v_mfma_f32_16x16x32_bf16 v[96:99], v[174:177], v[190:193], 0
	v_rcp_f32_e32 v232, v232
	v_rcp_f32_e32 v233, v233
	v_rcp_f32_e32 v234, v234
	v_rcp_f32_e32 v235, v235
	v_rcp_f32_e32 v236, v236
	v_mfma_f32_16x16x32_bf16 v[88:91], v[166:169], v[198:201], 0
	v_rcp_f32_e32 v237, v237
	s_add_u32 vcc_lo, s100, 0xdc000
	s_addc_u32 vcc_hi, s101, 0
	v_pk_mul_f32 v[24:25], v[230:231], v[24:25]
	v_pk_mul_f32 v[26:27], v[232:233], v[26:27]
	v_mfma_f32_16x16x32_bf16 v[80:83], v[174:177], v[198:201], 0
	v_pk_mul_f32 v[16:17], v[234:235], v[16:17]
	v_pk_mul_f32 v[18:19], v[236:237], v[18:19]
	v_cvt_pk_bf16_f32 v238, v24, v25
	v_cvt_pk_bf16_f32 v239, v26, v27
	v_mfma_f32_16x16x32_bf16 v[72:75], v[166:169], v[206:209], 0
	v_cvt_pk_bf16_f32 v240, v16, v17
	v_cvt_pk_bf16_f32 v241, v18, v19
	global_store_dwordx4 v224, v[238:241], vcc
	v_exp_f32_e64 v242, -v12
	v_exp_f32_e64 v243, -v13
	v_mfma_f32_16x16x32_bf16 v[64:67], v[174:177], v[206:209], 0
	v_exp_f32_e64 v244, -v14
	v_exp_f32_e64 v245, -v15
	v_exp_f32_e64 v246, -v4
	v_exp_f32_e64 v247, -v5
	v_exp_f32_e64 v248, -v6
	v_mfma_f32_16x16x32_bf16 v[120:123], v[170:173], v[186:189], v[120:123]
	v_exp_f32_e64 v249, -v7
	v_pk_mul_f32 v[8:9], v[12:13], v[8:9]
	v_pk_mul_f32 v[10:11], v[14:15], v[10:11]
	v_pk_mul_f32 v[0:1], v[4:5], v[0:1]
	v_mfma_f32_16x16x32_bf16 v[112:115], v[178:181], v[186:189], v[112:115]
	v_pk_mul_f32 v[2:3], v[6:7], v[2:3]
	v_pk_add_f32 v[242:243], v[242:243], 1.0 op_sel_hi:[1,0]
	v_pk_add_f32 v[244:245], v[244:245], 1.0 op_sel_hi:[1,0]
	v_pk_add_f32 v[246:247], v[246:247], 1.0 op_sel_hi:[1,0]
	v_pk_add_f32 v[248:249], v[248:249], 1.0 op_sel_hi:[1,0]
	v_mfma_f32_16x16x32_bf16 v[104:107], v[170:173], v[194:197], v[104:107]
	v_rcp_f32_e32 v242, v242
	v_rcp_f32_e32 v243, v243
	v_rcp_f32_e32 v244, v244
	v_rcp_f32_e32 v245, v245
	v_rcp_f32_e32 v246, v246
	v_mfma_f32_16x16x32_bf16 v[96:99], v[178:181], v[194:197], v[96:99]
	v_rcp_f32_e32 v247, v247
	v_rcp_f32_e32 v248, v248
	v_rcp_f32_e32 v249, v249
	s_add_u32 vcc_lo, s100, 0xf2000
	v_mfma_f32_16x16x32_bf16 v[88:91], v[170:173], v[202:205], v[88:91]
	s_addc_u32 vcc_hi, s101, 0
	v_pk_mul_f32 v[8:9], v[242:243], v[8:9]
	v_pk_mul_f32 v[10:11], v[244:245], v[10:11]
	v_pk_mul_f32 v[0:1], v[246:247], v[0:1]
	v_pk_mul_f32 v[2:3], v[248:249], v[2:3]
	v_mfma_f32_16x16x32_bf16 v[80:83], v[178:181], v[202:205], v[80:83]
	v_cvt_pk_bf16_f32 v250, v8, v9
	v_cvt_pk_bf16_f32 v251, v10, v11
	v_cvt_pk_bf16_f32 v252, v0, v1
	v_cvt_pk_bf16_f32 v253, v2, v3
	global_store_dwordx4 v224, v[250:253], vcc
	v_mfma_f32_16x16x32_bf16 v[72:75], v[170:173], v[210:213], v[72:75]
	v_mfma_f32_16x16x32_bf16 v[64:67], v[178:181], v[210:213], v[64:67]
	s_barrier
	s_setprio 0
.Lsw1_join:
	s_add_i32 s82, s73, s56
	v_lshl_add_u64 v[214:215], s[50:51], 0, v[132:133]
	s_mov_b32 m0, s82
	ds_read_b128 v[182:185], v149 offset:16384
	ds_read_b128 v[186:189], v149 offset:17408
	ds_read_b128 v[190:193], v149 offset:18432
	ds_read_b128 v[194:197], v149 offset:19456
	ds_read_b128 v[198:201], v149 offset:20480
	ds_read_b128 v[202:205], v149 offset:21504
	ds_read_b128 v[206:209], v149 offset:22528
	ds_read_b128 v[210:213], v149 offset:23552
	global_load_lds_dwordx4 v[214:215], off
	s_add_i32 m0, s82, 0x2000
	s_add_u32 s88, s50, 0x40000
	v_lshl_add_u64 v[216:217], s[50:51], 0, v[128:129]
	s_addc_u32 s89, s51, 0
	s_add_i32 s82, s74, s56
	global_load_lds_dwordx4 v[216:217], off
	v_lshl_add_u64 v[218:219], s[88:89], 0, v[132:133]
	s_mov_b32 m0, s82
	v_lshl_add_u64 v[220:221], s[52:53], 0, v[130:131]
	global_load_lds_dwordx4 v[218:219], off
	v_lshl_add_u64 v[218:219], s[88:89], 0, v[128:129]
	s_add_i32 m0, s82, 0x2000
	s_nop 0
	global_load_lds_dwordx4 v[218:219], off
	v_lshl_add_u64 v[218:219], s[52:53], 0, v[134:135]
	s_mov_b32 m0, s47
	s_nop 0
	global_load_lds_dwordx4 v[218:219], off
	s_mov_b32 m0, s59
	s_nop 0
	global_load_lds_dwordx4 v[220:221], off
	s_waitcnt vmcnt(8)
	s_waitcnt lgkmcnt(0)
	s_setprio 1
	s_barrier
	v_mfma_f32_16x16x32_bf16 v[60:63], v[150:153], v[182:185], 0
	v_mfma_f32_16x16x32_bf16 v[52:55], v[158:161], v[182:185], 0
	v_mfma_f32_16x16x32_bf16 v[44:47], v[150:153], v[190:193], 0
	v_mfma_f32_16x16x32_bf16 v[36:39], v[158:161], v[190:193], 0
	v_mfma_f32_16x16x32_bf16 v[28:31], v[150:153], v[198:201], 0
	v_mfma_f32_16x16x32_bf16 v[20:23], v[158:161], v[198:201], 0
	v_mfma_f32_16x16x32_bf16 v[12:15], v[150:153], v[206:209], 0
	v_mfma_f32_16x16x32_bf16 v[4:7], v[158:161], v[206:209], 0
	v_mfma_f32_16x16x32_bf16 v[60:63], v[154:157], v[186:189], v[60:63]
	v_mfma_f32_16x16x32_bf16 v[52:55], v[162:165], v[186:189], v[52:55]
	v_mfma_f32_16x16x32_bf16 v[44:47], v[154:157], v[194:197], v[44:47]
	v_mfma_f32_16x16x32_bf16 v[36:39], v[162:165], v[194:197], v[36:39]
	v_mfma_f32_16x16x32_bf16 v[28:31], v[154:157], v[202:205], v[28:31]
	v_mfma_f32_16x16x32_bf16 v[20:23], v[162:165], v[202:205], v[20:23]
	v_mfma_f32_16x16x32_bf16 v[12:15], v[154:157], v[210:213], v[12:15]
	v_mfma_f32_16x16x32_bf16 v[4:7], v[162:165], v[210:213], v[4:7]
	v_mfma_f32_16x16x32_bf16 v[56:59], v[166:169], v[182:185], 0
	v_mfma_f32_16x16x32_bf16 v[48:51], v[174:177], v[182:185], 0
	v_mfma_f32_16x16x32_bf16 v[40:43], v[166:169], v[190:193], 0
	v_mfma_f32_16x16x32_bf16 v[32:35], v[174:177], v[190:193], 0
	v_mfma_f32_16x16x32_bf16 v[24:27], v[166:169], v[198:201], 0
	v_mfma_f32_16x16x32_bf16 v[16:19], v[174:177], v[198:201], 0
	v_mfma_f32_16x16x32_bf16 v[8:11], v[166:169], v[206:209], 0
	v_mfma_f32_16x16x32_bf16 v[0:3], v[174:177], v[206:209], 0
	v_mfma_f32_16x16x32_bf16 v[56:59], v[170:173], v[186:189], v[56:59]
	v_mfma_f32_16x16x32_bf16 v[48:51], v[178:181], v[186:189], v[48:51]
	v_mfma_f32_16x16x32_bf16 v[40:43], v[170:173], v[194:197], v[40:43]
	v_mfma_f32_16x16x32_bf16 v[32:35], v[178:181], v[194:197], v[32:35]
	v_mfma_f32_16x16x32_bf16 v[24:27], v[170:173], v[202:205], v[24:27]
	v_mfma_f32_16x16x32_bf16 v[16:19], v[178:181], v[202:205], v[16:19]
	v_mfma_f32_16x16x32_bf16 v[8:11], v[170:173], v[210:213], v[8:11]
	v_mfma_f32_16x16x32_bf16 v[0:3], v[178:181], v[210:213], v[0:3]
	s_barrier
	s_setprio 0
	s_add_i32 s82, 0, 0x18000
	s_add_i32 s85, 0, 0x1c000
	v_add_u32_e32 v162, s82, v145
	v_add_u32_e32 v178, s85, v145
	ds_read_b128 v[150:153], v162
	ds_read_b128 v[154:157], v162 offset:1024
	ds_read_b128 v[158:161], v162 offset:2048
	ds_read_b128 v[162:165], v162 offset:3072
	ds_read_b128 v[166:169], v178
	ds_read_b128 v[170:173], v178 offset:1024
	ds_read_b128 v[174:177], v178 offset:2048
	ds_read_b128 v[178:181], v178 offset:3072
	s_add_u32 s52, s52, 0x40000
	s_addc_u32 s53, s53, 0
	s_mov_b32 m0, s66
	v_lshl_add_u64 v[222:223], s[52:53], 0, v[134:135]
	ds_read_b128 v[182:185], v149 offset:32768
	ds_read_b128 v[186:189], v149 offset:33792
	ds_read_b128 v[190:193], v149 offset:34816
	ds_read_b128 v[194:197], v149 offset:35840
	ds_read_b128 v[198:201], v149 offset:36864
	ds_read_b128 v[202:205], v149 offset:37888
	ds_read_b128 v[206:209], v149 offset:38912
	ds_read_b128 v[210:213], v149 offset:39936
	global_load_lds_dwordx4 v[222:223], off
	v_lshl_add_u64 v[222:223], s[52:53], 0, v[130:131]
	s_mov_b32 m0, s67
	s_nop 0
	global_load_lds_dwordx4 v[222:223], off
	s_waitcnt vmcnt(8)
	s_waitcnt lgkmcnt(0)
	s_setprio 1
	s_barrier
	v_mfma_f32_16x16x32_bf16 v[124:127], v[150:153], v[182:185], v[124:127]
	v_mfma_f32_16x16x32_bf16 v[116:119], v[158:161], v[182:185], v[116:119]
	v_mfma_f32_16x16x32_bf16 v[108:111], v[150:153], v[190:193], v[108:111]
	v_mfma_f32_16x16x32_bf16 v[100:103], v[158:161], v[190:193], v[100:103]
	v_mfma_f32_16x16x32_bf16 v[92:95], v[150:153], v[198:201], v[92:95]
	v_mfma_f32_16x16x32_bf16 v[84:87], v[158:161], v[198:201], v[84:87]
	v_mfma_f32_16x16x32_bf16 v[76:79], v[150:153], v[206:209], v[76:79]
	v_mfma_f32_16x16x32_bf16 v[68:71], v[158:161], v[206:209], v[68:71]
	v_mfma_f32_16x16x32_bf16 v[124:127], v[154:157], v[186:189], v[124:127]
	v_mfma_f32_16x16x32_bf16 v[116:119], v[162:165], v[186:189], v[116:119]
	v_mfma_f32_16x16x32_bf16 v[108:111], v[154:157], v[194:197], v[108:111]
	v_mfma_f32_16x16x32_bf16 v[100:103], v[162:165], v[194:197], v[100:103]
	v_mfma_f32_16x16x32_bf16 v[92:95], v[154:157], v[202:205], v[92:95]
	v_mfma_f32_16x16x32_bf16 v[84:87], v[162:165], v[202:205], v[84:87]
	v_mfma_f32_16x16x32_bf16 v[76:79], v[154:157], v[210:213], v[76:79]
	v_mfma_f32_16x16x32_bf16 v[68:71], v[162:165], v[210:213], v[68:71]
	v_mfma_f32_16x16x32_bf16 v[120:123], v[166:169], v[182:185], v[120:123]
	v_mfma_f32_16x16x32_bf16 v[112:115], v[174:177], v[182:185], v[112:115]
	v_mfma_f32_16x16x32_bf16 v[104:107], v[166:169], v[190:193], v[104:107]
	v_mfma_f32_16x16x32_bf16 v[96:99], v[174:177], v[190:193], v[96:99]
	v_mfma_f32_16x16x32_bf16 v[88:91], v[166:169], v[198:201], v[88:91]
	v_mfma_f32_16x16x32_bf16 v[80:83], v[174:177], v[198:201], v[80:83]
	v_mfma_f32_16x16x32_bf16 v[72:75], v[166:169], v[206:209], v[72:75]
	v_mfma_f32_16x16x32_bf16 v[64:67], v[174:177], v[206:209], v[64:67]
	v_mfma_f32_16x16x32_bf16 v[120:123], v[170:173], v[186:189], v[120:123]
	v_mfma_f32_16x16x32_bf16 v[112:115], v[178:181], v[186:189], v[112:115]
	v_mfma_f32_16x16x32_bf16 v[104:107], v[170:173], v[194:197], v[104:107]
	v_mfma_f32_16x16x32_bf16 v[96:99], v[178:181], v[194:197], v[96:99]
	v_mfma_f32_16x16x32_bf16 v[88:91], v[170:173], v[202:205], v[88:91]
	v_mfma_f32_16x16x32_bf16 v[80:83], v[178:181], v[202:205], v[80:83]
	v_mfma_f32_16x16x32_bf16 v[72:75], v[170:173], v[210:213], v[72:75]
	v_mfma_f32_16x16x32_bf16 v[64:67], v[178:181], v[210:213], v[64:67]
	s_barrier
	s_setprio 0
	s_add_i32 s52, s82, s56
	v_lshl_add_u64 v[214:215], v[214:215], 0, s[10:11]
	s_mov_b32 m0, s52
	ds_read_b128 v[182:185], v149 offset:49152
	ds_read_b128 v[186:189], v149 offset:50176
	ds_read_b128 v[190:193], v149 offset:51200
	ds_read_b128 v[194:197], v149 offset:52224
	ds_read_b128 v[198:201], v149 offset:53248
	ds_read_b128 v[202:205], v149 offset:54272
	ds_read_b128 v[206:209], v149 offset:55296
	ds_read_b128 v[210:213], v149 offset:56320
	global_load_lds_dwordx4 v[214:215], off
	s_add_i32 m0, s52, 0x2000
	s_add_u32 s50, s50, 0x40080
	v_lshl_add_u64 v[214:215], v[216:217], 0, s[10:11]
	s_addc_u32 s51, s51, 0
	s_add_i32 s52, s85, s56
	global_load_lds_dwordx4 v[214:215], off
	v_lshl_add_u64 v[214:215], s[50:51], 0, v[132:133]
	s_mov_b32 m0, s52
	s_nop 0
	global_load_lds_dwordx4 v[214:215], off
	v_lshl_add_u64 v[214:215], s[50:51], 0, v[128:129]
	s_add_i32 m0, s52, 0x2000
	s_nop 0
	global_load_lds_dwordx4 v[214:215], off
	v_lshl_add_u64 v[214:215], v[218:219], 0, s[10:11]
	s_mov_b32 m0, s69
	s_nop 0
	global_load_lds_dwordx4 v[214:215], off
	v_lshl_add_u64 v[214:215], v[220:221], 0, s[10:11]
	s_mov_b32 m0, s70
	s_nop 0
	global_load_lds_dwordx4 v[214:215], off
	s_waitcnt vmcnt(8)
	s_waitcnt lgkmcnt(0)
	s_setprio 1
	s_barrier
	v_mfma_f32_16x16x32_bf16 v[60:63], v[150:153], v[182:185], v[60:63]
	v_mfma_f32_16x16x32_bf16 v[52:55], v[158:161], v[182:185], v[52:55]
	v_mfma_f32_16x16x32_bf16 v[44:47], v[150:153], v[190:193], v[44:47]
	v_mfma_f32_16x16x32_bf16 v[36:39], v[158:161], v[190:193], v[36:39]
	v_mfma_f32_16x16x32_bf16 v[28:31], v[150:153], v[198:201], v[28:31]
	v_mfma_f32_16x16x32_bf16 v[20:23], v[158:161], v[198:201], v[20:23]
	v_mfma_f32_16x16x32_bf16 v[12:15], v[150:153], v[206:209], v[12:15]
	v_mfma_f32_16x16x32_bf16 v[4:7], v[158:161], v[206:209], v[4:7]
	v_mfma_f32_16x16x32_bf16 v[60:63], v[154:157], v[186:189], v[60:63]
	v_mfma_f32_16x16x32_bf16 v[52:55], v[162:165], v[186:189], v[52:55]
	v_mfma_f32_16x16x32_bf16 v[44:47], v[154:157], v[194:197], v[44:47]
	v_mfma_f32_16x16x32_bf16 v[36:39], v[162:165], v[194:197], v[36:39]
	v_mfma_f32_16x16x32_bf16 v[28:31], v[154:157], v[202:205], v[28:31]
	v_mfma_f32_16x16x32_bf16 v[20:23], v[162:165], v[202:205], v[20:23]
	v_mfma_f32_16x16x32_bf16 v[12:15], v[154:157], v[210:213], v[12:15]
	v_mfma_f32_16x16x32_bf16 v[4:7], v[162:165], v[210:213], v[4:7]
	v_mfma_f32_16x16x32_bf16 v[56:59], v[166:169], v[182:185], v[56:59]
	v_mfma_f32_16x16x32_bf16 v[48:51], v[174:177], v[182:185], v[48:51]
	v_mfma_f32_16x16x32_bf16 v[40:43], v[166:169], v[190:193], v[40:43]
	v_mfma_f32_16x16x32_bf16 v[32:35], v[174:177], v[190:193], v[32:35]
	v_mfma_f32_16x16x32_bf16 v[24:27], v[166:169], v[198:201], v[24:27]
	v_mfma_f32_16x16x32_bf16 v[16:19], v[174:177], v[198:201], v[16:19]
	v_mfma_f32_16x16x32_bf16 v[8:11], v[166:169], v[206:209], v[8:11]
	v_mfma_f32_16x16x32_bf16 v[0:3], v[174:177], v[206:209], v[0:3]
	v_mfma_f32_16x16x32_bf16 v[56:59], v[170:173], v[186:189], v[56:59]
	v_mfma_f32_16x16x32_bf16 v[48:51], v[178:181], v[186:189], v[48:51]
	v_mfma_f32_16x16x32_bf16 v[40:43], v[170:173], v[194:197], v[40:43]
	v_mfma_f32_16x16x32_bf16 v[32:35], v[178:181], v[194:197], v[32:35]
	v_mfma_f32_16x16x32_bf16 v[24:27], v[170:173], v[202:205], v[24:27]
	v_mfma_f32_16x16x32_bf16 v[16:19], v[178:181], v[202:205], v[16:19]
	v_mfma_f32_16x16x32_bf16 v[8:11], v[170:173], v[210:213], v[8:11]
	v_mfma_f32_16x16x32_bf16 v[0:3], v[178:181], v[210:213], v[0:3]
	s_barrier
	s_setprio 0
	s_add_i32 s81, s81, 2
	s_add_u32 s48, s48, 0x100
	s_addc_u32 s49, s49, 0
	s_add_u32 s79, s79, 0x100
	s_addc_u32 s80, s80, 0
	s_cmp_gt_u32 s81, 13

.LBB0_144:
	s_nop 7
	s_nop 7
	s_lshl_b32 s98, s46, 8
	s_mul_i32 s98, s98, s75
	s_lshl_b32 s100, s76, 8
	s_add_u32 s98, s98, s100
	s_add_u32 s100, s24, s98
	s_addc_u32 s101, s25, 0
	v_mul_u32_u24_e32 v224, s75, v144
	v_lshl_add_u32 v224, v146, 1, v224
	v_exp_f32_e64 v230, -v124
	v_exp_f32_e64 v231, -v125
	v_exp_f32_e64 v232, -v126
	v_exp_f32_e64 v233, -v127
	v_exp_f32_e64 v234, -v116
	v_exp_f32_e64 v235, -v117
	v_exp_f32_e64 v236, -v118
	v_exp_f32_e64 v237, -v119
	v_pk_mul_f32 v[120:121], v[124:125], v[120:121]
	v_pk_mul_f32 v[122:123], v[126:127], v[122:123]
	v_pk_mul_f32 v[112:113], v[116:117], v[112:113]
	v_pk_mul_f32 v[114:115], v[118:119], v[114:115]
	v_pk_add_f32 v[230:231], v[230:231], 1.0 op_sel_hi:[1,0]
	v_pk_add_f32 v[232:233], v[232:233], 1.0 op_sel_hi:[1,0]
	v_pk_add_f32 v[234:235], v[234:235], 1.0 op_sel_hi:[1,0]
	v_pk_add_f32 v[236:237], v[236:237], 1.0 op_sel_hi:[1,0]
	v_rcp_f32_e32 v230, v230
	v_rcp_f32_e32 v231, v231
	v_rcp_f32_e32 v232, v232
	v_rcp_f32_e32 v233, v233
	v_rcp_f32_e32 v234, v234
	v_rcp_f32_e32 v235, v235
	v_rcp_f32_e32 v236, v236
	v_rcp_f32_e32 v237, v237
	s_add_u32 vcc_lo, s100, 0x0
	s_addc_u32 vcc_hi, s101, 0
	v_pk_mul_f32 v[120:121], v[230:231], v[120:121]
	v_pk_mul_f32 v[122:123], v[232:233], v[122:123]
	v_pk_mul_f32 v[112:113], v[234:235], v[112:113]
	v_pk_mul_f32 v[114:115], v[236:237], v[114:115]
	v_cvt_pk_bf16_f32 v238, v120, v121
	v_cvt_pk_bf16_f32 v239, v122, v123
	v_cvt_pk_bf16_f32 v240, v112, v113
	v_cvt_pk_bf16_f32 v241, v114, v115
	global_store_dwordx4 v224, v[238:241], vcc
	v_exp_f32_e64 v242, -v108
	v_exp_f32_e64 v243, -v109
	v_exp_f32_e64 v244, -v110
	v_exp_f32_e64 v245, -v111
	v_exp_f32_e64 v246, -v100
	v_exp_f32_e64 v247, -v101
	v_exp_f32_e64 v248, -v102
	v_exp_f32_e64 v249, -v103
	v_pk_mul_f32 v[104:105], v[108:109], v[104:105]
	v_pk_mul_f32 v[106:107], v[110:111], v[106:107]
	v_pk_mul_f32 v[96:97], v[100:101], v[96:97]
	v_pk_mul_f32 v[98:99], v[102:103], v[98:99]
	v_pk_add_f32 v[242:243], v[242:243], 1.0 op_sel_hi:[1,0]
	v_pk_add_f32 v[244:245], v[244:245], 1.0 op_sel_hi:[1,0]
	v_pk_add_f32 v[246:247], v[246:247], 1.0 op_sel_hi:[1,0]
	v_pk_add_f32 v[248:249], v[248:249], 1.0 op_sel_hi:[1,0]
	v_rcp_f32_e32 v242, v242
	v_rcp_f32_e32 v243, v243
	v_rcp_f32_e32 v244, v244
	v_rcp_f32_e32 v245, v245
	v_rcp_f32_e32 v246, v246
	v_rcp_f32_e32 v247, v247
	v_rcp_f32_e32 v248, v248
	v_rcp_f32_e32 v249, v249
	s_add_u32 vcc_lo, s100, 0x16000
	s_addc_u32 vcc_hi, s101, 0
	v_pk_mul_f32 v[104:105], v[242:243], v[104:105]
	v_pk_mul_f32 v[106:107], v[244:245], v[106:107]
	v_pk_mul_f32 v[96:97], v[246:247], v[96:97]
	v_pk_mul_f32 v[98:99], v[248:249], v[98:99]
	v_cvt_pk_bf16_f32 v250, v104, v105
	v_cvt_pk_bf16_f32 v251, v106, v107
	v_cvt_pk_bf16_f32 v252, v96, v97
	v_cvt_pk_bf16_f32 v253, v98, v99
	global_store_dwordx4 v224, v[250:253], vcc
	v_exp_f32_e64 v230, -v92
	v_exp_f32_e64 v231, -v93
	v_exp_f32_e64 v232, -v94
	v_exp_f32_e64 v233, -v95
	v_exp_f32_e64 v234, -v84
	v_exp_f32_e64 v235, -v85
	v_exp_f32_e64 v236, -v86
	v_exp_f32_e64 v237, -v87
	v_pk_mul_f32 v[88:89], v[92:93], v[88:89]
	v_pk_mul_f32 v[90:91], v[94:95], v[90:91]
	v_pk_mul_f32 v[80:81], v[84:85], v[80:81]
	v_pk_mul_f32 v[82:83], v[86:87], v[82:83]
	v_pk_add_f32 v[230:231], v[230:231], 1.0 op_sel_hi:[1,0]
	v_pk_add_f32 v[232:233], v[232:233], 1.0 op_sel_hi:[1,0]
	v_pk_add_f32 v[234:235], v[234:235], 1.0 op_sel_hi:[1,0]
	v_pk_add_f32 v[236:237], v[236:237], 1.0 op_sel_hi:[1,0]
	v_rcp_f32_e32 v230, v230
	v_rcp_f32_e32 v231, v231
	v_rcp_f32_e32 v232, v232
	v_rcp_f32_e32 v233, v233
	v_rcp_f32_e32 v234, v234
	v_rcp_f32_e32 v235, v235
	v_rcp_f32_e32 v236, v236
	v_rcp_f32_e32 v237, v237
	s_add_u32 vcc_lo, s100, 0x2c000
	s_addc_u32 vcc_hi, s101, 0
	v_pk_mul_f32 v[88:89], v[230:231], v[88:89]
	v_pk_mul_f32 v[90:91], v[232:233], v[90:91]
	v_pk_mul_f32 v[80:81], v[234:235], v[80:81]
	v_pk_mul_f32 v[82:83], v[236:237], v[82:83]
	v_cvt_pk_bf16_f32 v238, v88, v89
	v_cvt_pk_bf16_f32 v239, v90, v91
	v_cvt_pk_bf16_f32 v240, v80, v81
	v_cvt_pk_bf16_f32 v241, v82, v83
	global_store_dwordx4 v224, v[238:241], vcc
	v_exp_f32_e64 v242, -v76
	v_exp_f32_e64 v243, -v77
	v_exp_f32_e64 v244, -v78
	v_exp_f32_e64 v245, -v79
	v_exp_f32_e64 v246, -v68
	v_exp_f32_e64 v247, -v69
	v_exp_f32_e64 v248, -v70
	v_exp_f32_e64 v249, -v71
	v_pk_mul_f32 v[72:73], v[76:77], v[72:73]
	v_pk_mul_f32 v[74:75], v[78:79], v[74:75]
	v_pk_mul_f32 v[64:65], v[68:69], v[64:65]
	v_pk_mul_f32 v[66:67], v[70:71], v[66:67]
	v_pk_add_f32 v[242:243], v[242:243], 1.0 op_sel_hi:[1,0]
	v_pk_add_f32 v[244:245], v[244:245], 1.0 op_sel_hi:[1,0]
	v_pk_add_f32 v[246:247], v[246:247], 1.0 op_sel_hi:[1,0]
	v_pk_add_f32 v[248:249], v[248:249], 1.0 op_sel_hi:[1,0]
	v_rcp_f32_e32 v242, v242
	v_rcp_f32_e32 v243, v243
	v_rcp_f32_e32 v244, v244
	v_rcp_f32_e32 v245, v245
	v_rcp_f32_e32 v246, v246
	v_rcp_f32_e32 v247, v247
	v_rcp_f32_e32 v248, v248
	v_rcp_f32_e32 v249, v249
	s_add_u32 vcc_lo, s100, 0x42000
	s_addc_u32 vcc_hi, s101, 0
	v_pk_mul_f32 v[72:73], v[242:243], v[72:73]
	v_pk_mul_f32 v[74:75], v[244:245], v[74:75]
	v_pk_mul_f32 v[64:65], v[246:247], v[64:65]
	v_pk_mul_f32 v[66:67], v[248:249], v[66:67]
	v_cvt_pk_bf16_f32 v250, v72, v73
	v_cvt_pk_bf16_f32 v251, v74, v75
	v_cvt_pk_bf16_f32 v252, v64, v65
	v_cvt_pk_bf16_f32 v253, v66, v67
	global_store_dwordx4 v224, v[250:253], vcc
	s_mov_b32 s99, 1
	s_andn2_b64 vcc, exec, s[0:1]
	s_mov_b64 s[0:1], -1
	s_cbranch_vccnz .LBB0_137
	s_andn2_b64 vcc, exec, s[8:9]
	s_cbranch_vccnz .LBB0_136
	s_barrier
	s_branch .LBB0_136
.LBB0_147:
	s_cmp_eq_u32 s99, 1
	s_cbranch_scc0 .Lsw1_none
	s_nop 7
	s_nop 7
	v_exp_f32_e64 v230, -v60
	v_exp_f32_e64 v231, -v61
	v_exp_f32_e64 v232, -v62
	v_exp_f32_e64 v233, -v63
	v_exp_f32_e64 v234, -v52
	v_exp_f32_e64 v235, -v53
	v_exp_f32_e64 v236, -v54
	v_exp_f32_e64 v237, -v55
	v_pk_mul_f32 v[56:57], v[60:61], v[56:57]
	v_pk_mul_f32 v[58:59], v[62:63], v[58:59]
	v_pk_mul_f32 v[48:49], v[52:53], v[48:49]
	v_pk_mul_f32 v[50:51], v[54:55], v[50:51]
	v_pk_add_f32 v[230:231], v[230:231], 1.0 op_sel_hi:[1,0]
	v_pk_add_f32 v[232:233], v[232:233], 1.0 op_sel_hi:[1,0]
	v_pk_add_f32 v[234:235], v[234:235], 1.0 op_sel_hi:[1,0]
	v_pk_add_f32 v[236:237], v[236:237], 1.0 op_sel_hi:[1,0]
	v_rcp_f32_e32 v230, v230
	v_rcp_f32_e32 v231, v231
	v_rcp_f32_e32 v232, v232
	v_rcp_f32_e32 v233, v233
	v_rcp_f32_e32 v234, v234
	v_rcp_f32_e32 v235, v235
	v_rcp_f32_e32 v236, v236
	v_rcp_f32_e32 v237, v237
	s_add_u32 vcc_lo, s100, 0xb0000
	s_addc_u32 vcc_hi, s101, 0
	v_pk_mul_f32 v[56:57], v[230:231], v[56:57]
	v_pk_mul_f32 v[58:59], v[232:233], v[58:59]
	v_pk_mul_f32 v[48:49], v[234:235], v[48:49]
	v_pk_mul_f32 v[50:51], v[236:237], v[50:51]
	v_cvt_pk_bf16_f32 v238, v56, v57
	v_cvt_pk_bf16_f32 v239, v58, v59
	v_cvt_pk_bf16_f32 v240, v48, v49
	v_cvt_pk_bf16_f32 v241, v50, v51
	global_store_dwordx4 v224, v[238:241], vcc
	v_exp_f32_e64 v242, -v44
	v_exp_f32_e64 v243, -v45
	v_exp_f32_e64 v244, -v46
	v_exp_f32_e64 v245, -v47
	v_exp_f32_e64 v246, -v36
	v_exp_f32_e64 v247, -v37
	v_exp_f32_e64 v248, -v38
	v_exp_f32_e64 v249, -v39
	v_pk_mul_f32 v[40:41], v[44:45], v[40:41]
	v_pk_mul_f32 v[42:43], v[46:47], v[42:43]
	v_pk_mul_f32 v[32:33], v[36:37], v[32:33]
	v_pk_mul_f32 v[34:35], v[38:39], v[34:35]
	v_pk_add_f32 v[242:243], v[242:243], 1.0 op_sel_hi:[1,0]
	v_pk_add_f32 v[244:245], v[244:245], 1.0 op_sel_hi:[1,0]
	v_pk_add_f32 v[246:247], v[246:247], 1.0 op_sel_hi:[1,0]
	v_pk_add_f32 v[248:249], v[248:249], 1.0 op_sel_hi:[1,0]
	v_rcp_f32_e32 v242, v242
	v_rcp_f32_e32 v243, v243
	v_rcp_f32_e32 v244, v244
	v_rcp_f32_e32 v245, v245
	v_rcp_f32_e32 v246, v246
	v_rcp_f32_e32 v247, v247
	v_rcp_f32_e32 v248, v248
	v_rcp_f32_e32 v249, v249
	s_add_u32 vcc_lo, s100, 0xc6000
	s_addc_u32 vcc_hi, s101, 0
	v_pk_mul_f32 v[40:41], v[242:243], v[40:41]
	v_pk_mul_f32 v[42:43], v[244:245], v[42:43]
	v_pk_mul_f32 v[32:33], v[246:247], v[32:33]
	v_pk_mul_f32 v[34:35], v[248:249], v[34:35]
	v_cvt_pk_bf16_f32 v250, v40, v41
	v_cvt_pk_bf16_f32 v251, v42, v43
	v_cvt_pk_bf16_f32 v252, v32, v33
	v_cvt_pk_bf16_f32 v253, v34, v35
	global_store_dwordx4 v224, v[250:253], vcc
	v_exp_f32_e64 v230, -v28
	v_exp_f32_e64 v231, -v29
	v_exp_f32_e64 v232, -v30
	v_exp_f32_e64 v233, -v31
	v_exp_f32_e64 v234, -v20
	v_exp_f32_e64 v235, -v21
	v_exp_f32_e64 v236, -v22
	v_exp_f32_e64 v237, -v23
	v_pk_mul_f32 v[24:25], v[28:29], v[24:25]
	v_pk_mul_f32 v[26:27], v[30:31], v[26:27]
	v_pk_mul_f32 v[16:17], v[20:21], v[16:17]
	v_pk_mul_f32 v[18:19], v[22:23], v[18:19]
	v_pk_add_f32 v[230:231], v[230:231], 1.0 op_sel_hi:[1,0]
	v_pk_add_f32 v[232:233], v[232:233], 1.0 op_sel_hi:[1,0]
	v_pk_add_f32 v[234:235], v[234:235], 1.0 op_sel_hi:[1,0]
	v_pk_add_f32 v[236:237], v[236:237], 1.0 op_sel_hi:[1,0]
	v_rcp_f32_e32 v230, v230
	v_rcp_f32_e32 v231, v231
	v_rcp_f32_e32 v232, v232
	v_rcp_f32_e32 v233, v233
	v_rcp_f32_e32 v234, v234
	v_rcp_f32_e32 v235, v235
	v_rcp_f32_e32 v236, v236
	v_rcp_f32_e32 v237, v237
	s_add_u32 vcc_lo, s100, 0xdc000
	s_addc_u32 vcc_hi, s101, 0
	v_pk_mul_f32 v[24:25], v[230:231], v[24:25]
	v_pk_mul_f32 v[26:27], v[232:233], v[26:27]
	v_pk_mul_f32 v[16:17], v[234:235], v[16:17]
	v_pk_mul_f32 v[18:19], v[236:237], v[18:19]
	v_cvt_pk_bf16_f32 v238, v24, v25
	v_cvt_pk_bf16_f32 v239, v26, v27
	v_cvt_pk_bf16_f32 v240, v16, v17
	v_cvt_pk_bf16_f32 v241, v18, v19
	global_store_dwordx4 v224, v[238:241], vcc
	v_exp_f32_e64 v242, -v12
	v_exp_f32_e64 v243, -v13
	v_exp_f32_e64 v244, -v14
	v_exp_f32_e64 v245, -v15
	v_exp_f32_e64 v246, -v4
	v_exp_f32_e64 v247, -v5
	v_exp_f32_e64 v248, -v6
	v_exp_f32_e64 v249, -v7
	v_pk_mul_f32 v[8:9], v[12:13], v[8:9]
	v_pk_mul_f32 v[10:11], v[14:15], v[10:11]
	v_pk_mul_f32 v[0:1], v[4:5], v[0:1]
	v_pk_mul_f32 v[2:3], v[6:7], v[2:3]
	v_pk_add_f32 v[242:243], v[242:243], 1.0 op_sel_hi:[1,0]
	v_pk_add_f32 v[244:245], v[244:245], 1.0 op_sel_hi:[1,0]
	v_pk_add_f32 v[246:247], v[246:247], 1.0 op_sel_hi:[1,0]
	v_pk_add_f32 v[248:249], v[248:249], 1.0 op_sel_hi:[1,0]
	v_rcp_f32_e32 v242, v242
	v_rcp_f32_e32 v243, v243
	v_rcp_f32_e32 v244, v244
	v_rcp_f32_e32 v245, v245
	v_rcp_f32_e32 v246, v246
	v_rcp_f32_e32 v247, v247
	v_rcp_f32_e32 v248, v248
	v_rcp_f32_e32 v249, v249
	s_add_u32 vcc_lo, s100, 0xf2000
	s_addc_u32 vcc_hi, s101, 0
	v_pk_mul_f32 v[8:9], v[242:243], v[8:9]
	v_pk_mul_f32 v[10:11], v[244:245], v[10:11]
	v_pk_mul_f32 v[0:1], v[246:247], v[0:1]
	v_pk_mul_f32 v[2:3], v[248:249], v[2:3]
	v_cvt_pk_bf16_f32 v250, v8, v9
	v_cvt_pk_bf16_f32 v251, v10, v11
	v_cvt_pk_bf16_f32 v252, v0, v1
	v_cvt_pk_bf16_f32 v253, v2, v3
	global_store_dwordx4 v224, v[250:253], vcc
	s_mov_b32 s99, 0
